# code alignment shift: +16 bytes of s_nop at kernel entry
# baseline (speedup 1.0000x reference)
_Z10fwd_kernel4Args:
	s_nop 0
	s_nop 0
	s_nop 0
	s_nop 0
	s_load_dwordx16 s[48:63], s[0:1], 0xc0
	s_load_dwordx2 s[96:97], s[0:1], 0x100
	s_load_dword s33, s[0:1], 0x108
	s_add_u32 s4, s0, 0x108
	s_addc_u32 s5, s1, 0
	v_and_b32_e32 v190, 0x3ff, v0
	v_writelane_b32 v254, s4, 0
	v_readfirstlane_b32 s3, v190
	v_cmp_eq_u32_e64 s[6:7], 0, v190
	v_writelane_b32 v254, s5, 1
	s_mov_b64 s[4:5], exec
	v_writelane_b32 v254, s6, 2
	s_nop 1
	v_writelane_b32 v254, s7, 3
	s_and_b64 s[6:7], s[4:5], s[6:7]
	s_mov_b64 exec, s[6:7]
	s_cbranch_execz .LBB0_2
	s_add_i32 s6, 0, 0x23fc0
	v_mov_b32_e32 v1, 0
	v_mov_b32_e32 v2, s6
	s_add_i32 s6, 0, 0x23fc4
	ds_write_b32 v2, v1
	v_mov_b32_e32 v2, s6
	ds_write_b32 v2, v1
